# attention tile bodies: serialized ds_read->wait->mfma chains re-issued as groups of up to 6 LDS reads into spare registers with counted waits
# speedup vs baseline: 1.0039x; 1.0039x over previous
.LBB0_1194:
	s_nop 4
	v_add_u32_e32 v94, 0x4000, v201
	ds_read2_b64 v[90:93], v94 offset0:128 offset1:132
	v_cvt_pk_bf16_f32 v86, v98, v99
	v_cvt_pk_bf16_f32 v87, v100, v101
	v_cvt_pk_bf16_f32 v88, v102, v103
	v_cvt_pk_bf16_f32 v89, v104, v105
	v_add_u32_e32 v95, 0x4800, v201
	v_add_u32_e32 v96, 0x5000, v201
	v_mul_f32_e32 v85, v97, v203
	v_add_u32_e32 v97, 0x5800, v201
	s_waitcnt lgkmcnt(0)
	v_mfma_f32_16x16x32_bf16 v[74:77], v[90:93], v[86:89], v[74:77]
	ds_read2_b64 v[90:93], v95 offset0:160 offset1:164
	v_add_u32_e32 v98, 0x6800, v201
	v_add_u32_e32 v99, 0x7000, v201
	v_add_u32_e32 v100, 0x7800, v201
	v_add_u32_e32 v101, 0x8000, v201
	v_cvt_pk_bf16_f32 v82, v106, v107
	v_cvt_pk_bf16_f32 v83, v108, v109
	v_cvt_pk_bf16_f32 v84, v164, v165
	s_waitcnt lgkmcnt(0)
	v_mfma_f32_16x16x32_bf16 v[78:81], v[90:93], v[86:89], v[78:81]
	ds_read2_b64 v[90:93], v96 offset0:192 offset1:196
	v_cvt_pk_bf16_f32 v85, v202, v85
	s_add_i32 s5, s5, 64
	s_sub_i32 s8, s8, 64
	s_add_i32 s10, s10, 1
	v_lshl_add_u64 v[156:157], v[156:157], 0, s[44:45]
	v_lshl_add_u64 v[158:159], v[158:159], 0, s[44:45]
	s_waitcnt lgkmcnt(0)
	v_mfma_f32_16x16x32_bf16 v[70:73], v[90:93], v[86:89], v[70:73]
	ds_read2_b64 v[90:93], v97 offset0:224 offset1:228
	v_lshl_add_u64 v[160:161], v[160:161], 0, s[44:45]
	v_lshl_add_u64 v[162:163], v[162:163], 0, s[44:45]
	s_cmpk_lg_i32 s5, 0x100
	s_waitcnt lgkmcnt(0)
	v_mfma_f32_16x16x32_bf16 v[66:69], v[90:93], v[86:89], v[66:69]
	ds_read2_b64 v[208:211], v98 offset1:4
	ds_read2_b64 v[212:215], v99 offset0:32 offset1:36
	ds_read2_b64 v[216:219], v100 offset0:64 offset1:68
	ds_read2_b64 v[220:223], v101 offset0:96 offset1:100
	ds_read2_b64 v[224:227], v94 offset0:136 offset1:140
	ds_read2_b64 v[228:231], v95 offset0:168 offset1:172
	s_waitcnt lgkmcnt(5)
	v_mfma_f32_16x16x32_bf16 v[62:65], v[208:211], v[86:89], v[62:65]
	s_waitcnt lgkmcnt(4)
	v_mfma_f32_16x16x32_bf16 v[58:61], v[212:215], v[86:89], v[58:61]
	s_waitcnt lgkmcnt(3)
	v_mfma_f32_16x16x32_bf16 v[54:57], v[216:219], v[86:89], v[54:57]
	s_waitcnt lgkmcnt(2)
	v_mfma_f32_16x16x32_bf16 v[0:3], v[220:223], v[86:89], v[0:3]
	s_waitcnt lgkmcnt(1)
	v_mfma_f32_16x16x32_bf16 v[74:77], v[224:227], v[82:85], v[74:77]
	s_waitcnt lgkmcnt(0)
	v_mfma_f32_16x16x32_bf16 v[78:81], v[228:231], v[82:85], v[78:81]
	ds_read2_b64 v[208:211], v96 offset0:200 offset1:204
	ds_read2_b64 v[212:215], v97 offset0:232 offset1:236
	ds_read2_b64 v[216:219], v98 offset0:8 offset1:12
	ds_read2_b64 v[220:223], v99 offset0:40 offset1:44
	ds_read2_b64 v[224:227], v100 offset0:72 offset1:76
	ds_read2_b64 v[228:231], v101 offset0:104 offset1:108
	s_waitcnt lgkmcnt(5)
	v_mfma_f32_16x16x32_bf16 v[70:73], v[208:211], v[82:85], v[70:73]
	s_waitcnt lgkmcnt(4)
	v_mfma_f32_16x16x32_bf16 v[66:69], v[212:215], v[82:85], v[66:69]
	s_waitcnt lgkmcnt(3)
	v_mfma_f32_16x16x32_bf16 v[62:65], v[216:219], v[82:85], v[62:65]
	s_waitcnt lgkmcnt(2)
	v_mfma_f32_16x16x32_bf16 v[58:61], v[220:223], v[82:85], v[58:61]
	s_waitcnt lgkmcnt(1)
	v_mfma_f32_16x16x32_bf16 v[54:57], v[224:227], v[82:85], v[54:57]
	s_waitcnt lgkmcnt(0)
	v_mfma_f32_16x16x32_bf16 v[0:3], v[228:231], v[82:85], v[0:3]
	s_cbranch_scc0 .LBB0_1269

.LBB0_1197:
	ds_read_b128 v[82:85], v200
	ds_read_b128 v[86:89], v200 offset:64
	s_mov_b64 s[0:1], -1
	s_cmp_ge_u32 s10, s2
	s_waitcnt lgkmcnt(1)
	v_mfma_f32_16x16x32_bf16 v[82:85], v[82:85], v[6:9], 0
	ds_read_b128 v[90:93], v200 offset:4416
	ds_read_b128 v[94:97], v200 offset:8768
	ds_read_b128 v[98:101], v200 offset:13120
	s_waitcnt lgkmcnt(3)
	v_mfma_f32_16x16x32_bf16 v[82:85], v[86:89], v[10:13], v[82:85]
	ds_read_b128 v[208:211], v200 offset:128
	ds_read_b128 v[212:215], v200 offset:192
	ds_read_b128 v[216:219], v200 offset:4352
	s_waitcnt lgkmcnt(2)
	v_mfma_f32_16x16x32_bf16 v[82:85], v[208:211], v[14:17], v[82:85]
	s_waitcnt lgkmcnt(1)
	v_mfma_f32_16x16x32_bf16 v[82:85], v[212:215], v[18:21], v[82:85]
	s_waitcnt lgkmcnt(0)
	v_mfma_f32_16x16x32_bf16 v[86:89], v[216:219], v[6:9], 0
	v_mfma_f32_16x16x32_bf16 v[86:89], v[90:93], v[10:13], v[86:89]
	ds_read_b128 v[208:211], v200 offset:4480
	ds_read_b128 v[212:215], v200 offset:4544
	ds_read_b128 v[216:219], v200 offset:8704
	s_waitcnt lgkmcnt(2)
	v_mfma_f32_16x16x32_bf16 v[86:89], v[208:211], v[14:17], v[86:89]
	s_waitcnt lgkmcnt(1)
	v_mfma_f32_16x16x32_bf16 v[86:89], v[212:215], v[18:21], v[86:89]
	s_waitcnt lgkmcnt(0)
	v_mfma_f32_16x16x32_bf16 v[90:93], v[216:219], v[6:9], 0
	v_mfma_f32_16x16x32_bf16 v[90:93], v[94:97], v[10:13], v[90:93]
	ds_read_b128 v[208:211], v200 offset:8832
	ds_read_b128 v[212:215], v200 offset:8896
	ds_read_b128 v[216:219], v200 offset:13056
	s_waitcnt lgkmcnt(2)
	v_mfma_f32_16x16x32_bf16 v[90:93], v[208:211], v[14:17], v[90:93]
	s_waitcnt lgkmcnt(1)
	v_mfma_f32_16x16x32_bf16 v[90:93], v[212:215], v[18:21], v[90:93]
	s_waitcnt lgkmcnt(0)
	v_mfma_f32_16x16x32_bf16 v[94:97], v[216:219], v[6:9], 0
	v_mfma_f32_16x16x32_bf16 v[94:97], v[98:101], v[10:13], v[94:97]
	ds_read_b128 v[208:211], v200 offset:13184
	ds_read_b128 v[212:215], v200 offset:13248
	s_waitcnt lgkmcnt(1)
	v_mfma_f32_16x16x32_bf16 v[94:97], v[208:211], v[14:17], v[94:97]
	s_waitcnt lgkmcnt(0)
	v_mfma_f32_16x16x32_bf16 v[94:97], v[212:215], v[18:21], v[94:97]
	s_cbranch_scc0 .LBB0_1267
	s_cmp_gt_u32 s10, s2
	s_cbranch_scc1 .LBB0_1264
	v_add_u32_e32 v100, s8, v175
	v_cmp_gt_i32_e32 vcc, 1, v100
	s_and_saveexec_b64 s[0:1], vcc
	s_xor_b64 s[0:1], exec, s[0:1]
	s_cbranch_execz .LBB0_1201
	v_add_u32_e32 v98, s5, v177
	v_cvt_f32_u32_e32 v98, v98
	v_cmp_ne_u32_e32 vcc, s5, v175
	v_mul_f32_e32 v98, v169, v98
	v_exp_f32_e32 v98, v98
	s_nop 0
	v_cndmask_b32_e32 v98, 2.0, v98, vcc

.LBB0_1404:
	v_sub_f32_e32 v4, v121, v6
	v_mul_f32_e32 v4, 0x3fb8aa3b, v4
	v_exp_f32_e32 v4, v4
	s_or_b64 s[60:61], s[60:61], s[96:97]
	s_and_b64 vcc, exec, s[60:61]
	v_add_u32_e32 v79, 0x4800, v97
	v_pk_mul_f32 v[58:59], v[58:59], v[4:5] op_sel_hi:[1,0]
	v_pk_mul_f32 v[56:57], v[56:57], v[4:5] op_sel_hi:[1,0]
	v_pk_mul_f32 v[54:55], v[54:55], v[4:5] op_sel_hi:[1,0]
	v_pk_mul_f32 v[52:53], v[52:53], v[4:5] op_sel_hi:[1,0]
	v_pk_mul_f32 v[50:51], v[50:51], v[4:5] op_sel_hi:[1,0]
	v_pk_mul_f32 v[48:49], v[48:49], v[4:5] op_sel_hi:[1,0]
	v_pk_mul_f32 v[46:47], v[46:47], v[4:5] op_sel_hi:[1,0]
	v_pk_mul_f32 v[44:45], v[44:45], v[4:5] op_sel_hi:[1,0]
	v_add_u32_e32 v78, 0x5000, v97
	v_add_u32_e32 v71, 0x5800, v97
	v_add_u32_e32 v62, 0x6000, v97
	s_cbranch_vccnz .LBB0_1406
	ds_read2_b64 v[122:125], v79 offset1:4
	v_cvt_pk_bf16_f32 v72, v72, v73
	v_cvt_pk_bf16_f32 v73, v74, v75
	v_cvt_pk_bf16_f32 v74, v64, v70
	v_cvt_pk_bf16_f32 v75, v76, v77
	s_waitcnt lgkmcnt(0)
	s_nop 0
	v_mfma_f32_16x16x32_bf16 v[56:59], v[122:125], v[72:75], v[56:59]
	ds_read2_b64 v[132:135], v78 offset0:32 offset1:36
	ds_read2_b64 v[136:139], v71 offset0:64 offset1:68
	ds_read2_b64 v[140:143], v62 offset0:96 offset1:100
	s_waitcnt lgkmcnt(2)
	v_mfma_f32_16x16x32_bf16 v[52:55], v[132:135], v[72:75], v[52:55]
	s_waitcnt lgkmcnt(1)
	v_mfma_f32_16x16x32_bf16 v[48:51], v[136:139], v[72:75], v[48:51]
	s_waitcnt lgkmcnt(0)
	v_mfma_f32_16x16x32_bf16 v[44:47], v[140:143], v[72:75], v[44:47]

.LBB0_1468:
	v_sub_f32_e32 v6, v6, v121
	v_mul_f32_e32 v6, 0x3fb8aa3b, v6
	v_exp_f32_e32 v6, v6
	s_andn2_b64 vcc, exec, s[60:61]
	v_add_u32_e32 v122, 0x6800, v119
	v_add_u32_e32 v78, 0x7000, v119
	v_pk_mul_f32 v[58:59], v[58:59], v[6:7] op_sel_hi:[1,0]
	v_pk_mul_f32 v[56:57], v[56:57], v[6:7] op_sel_hi:[1,0]
	v_pk_mul_f32 v[54:55], v[54:55], v[6:7] op_sel_hi:[1,0]
	v_pk_mul_f32 v[52:53], v[52:53], v[6:7] op_sel_hi:[1,0]
	v_pk_mul_f32 v[50:51], v[50:51], v[6:7] op_sel_hi:[1,0]
	v_pk_mul_f32 v[48:49], v[48:49], v[6:7] op_sel_hi:[1,0]
	v_pk_mul_f32 v[46:47], v[46:47], v[6:7] op_sel_hi:[1,0]
	v_pk_mul_f32 v[44:45], v[44:45], v[6:7] op_sel_hi:[1,0]
	v_add_u32_e32 v74, 0x7800, v119
	v_add_u32_e32 v62, 0x8000, v119
	s_cbranch_vccnz .LBB0_1470
	ds_read2_b64 v[128:131], v122 offset0:128 offset1:132
	v_cvt_pk_bf16_f32 v124, v69, v71
	v_cvt_pk_bf16_f32 v125, v76, v77
	v_cvt_pk_bf16_f32 v126, v65, v73
	v_cvt_pk_bf16_f32 v127, v75, v79
	s_waitcnt lgkmcnt(0)
	s_nop 0
	v_mfma_f32_16x16x32_bf16 v[56:59], v[128:131], v[124:127], v[56:59]
	ds_read2_b64 v[132:135], v78 offset0:160 offset1:164
	ds_read2_b64 v[136:139], v74 offset0:192 offset1:196
	ds_read2_b64 v[140:143], v62 offset0:224 offset1:228
	s_waitcnt lgkmcnt(2)
	v_mfma_f32_16x16x32_bf16 v[52:55], v[132:135], v[124:127], v[52:55]
	s_waitcnt lgkmcnt(1)
	v_mfma_f32_16x16x32_bf16 v[48:51], v[136:139], v[124:127], v[48:51]
	s_waitcnt lgkmcnt(0)
	v_mfma_f32_16x16x32_bf16 v[44:47], v[140:143], v[124:127], v[44:47]

.LBB0_1478:
	s_nop 4
	v_add_u32_e32 v94, 0x4000, v203
	ds_read2_b64 v[90:93], v94 offset0:128 offset1:132
	v_cvt_pk_bf16_f32 v86, v98, v99
	v_cvt_pk_bf16_f32 v87, v100, v101
	v_cvt_pk_bf16_f32 v88, v102, v103
	v_cvt_pk_bf16_f32 v89, v104, v105
	v_add_u32_e32 v95, 0x4800, v203
	v_add_u32_e32 v96, 0x5000, v203
	v_mul_f32_e32 v85, v97, v205
	v_add_u32_e32 v97, 0x5800, v203
	s_waitcnt lgkmcnt(0)
	v_mfma_f32_16x16x32_bf16 v[6:9], v[90:93], v[86:89], v[6:9]
	ds_read2_b64 v[90:93], v95 offset0:160 offset1:164
	v_add_u32_e32 v98, 0x6800, v203
	v_add_u32_e32 v99, 0x7000, v203
	v_add_u32_e32 v100, 0x7800, v203
	v_add_u32_e32 v101, 0x8000, v203
	v_cvt_pk_bf16_f32 v82, v106, v107
	v_cvt_pk_bf16_f32 v83, v108, v109
	v_cvt_pk_bf16_f32 v84, v166, v167
	s_waitcnt lgkmcnt(0)
	v_mfma_f32_16x16x32_bf16 v[10:13], v[90:93], v[86:89], v[10:13]
	ds_read2_b64 v[90:93], v96 offset0:192 offset1:196
	v_cvt_pk_bf16_f32 v85, v204, v85
	s_add_i32 s11, s11, 64
	s_sub_i32 s9, s9, 64
	s_add_i32 s12, s12, 1
	v_lshl_add_u64 v[158:159], v[158:159], 0, s[44:45]
	v_lshl_add_u64 v[160:161], v[160:161], 0, s[44:45]
	s_waitcnt lgkmcnt(0)
	v_mfma_f32_16x16x32_bf16 v[34:37], v[90:93], v[86:89], v[34:37]
	ds_read2_b64 v[90:93], v97 offset0:224 offset1:228
	v_lshl_add_u64 v[162:163], v[162:163], 0, s[44:45]
	v_lshl_add_u64 v[164:165], v[164:165], 0, s[44:45]
	s_cmpk_eq_i32 s11, 0x400
	s_waitcnt lgkmcnt(0)
	v_mfma_f32_16x16x32_bf16 v[26:29], v[90:93], v[86:89], v[26:29]
	ds_read2_b64 v[208:211], v98 offset1:4
	ds_read2_b64 v[212:215], v99 offset0:32 offset1:36
	ds_read2_b64 v[216:219], v100 offset0:64 offset1:68
	ds_read2_b64 v[220:223], v101 offset0:96 offset1:100
	ds_read2_b64 v[224:227], v94 offset0:136 offset1:140
	ds_read2_b64 v[228:231], v95 offset0:168 offset1:172
	s_waitcnt lgkmcnt(5)
	v_mfma_f32_16x16x32_bf16 v[22:25], v[208:211], v[86:89], v[22:25]
	s_waitcnt lgkmcnt(4)
	v_mfma_f32_16x16x32_bf16 v[46:49], v[212:215], v[86:89], v[46:49]
	s_waitcnt lgkmcnt(3)
	v_mfma_f32_16x16x32_bf16 v[42:45], v[216:219], v[86:89], v[42:45]
	s_waitcnt lgkmcnt(2)
	v_mfma_f32_16x16x32_bf16 v[0:3], v[220:223], v[86:89], v[0:3]
	s_waitcnt lgkmcnt(1)
	v_mfma_f32_16x16x32_bf16 v[6:9], v[224:227], v[82:85], v[6:9]
	s_waitcnt lgkmcnt(0)
	v_mfma_f32_16x16x32_bf16 v[10:13], v[228:231], v[82:85], v[10:13]
	ds_read2_b64 v[208:211], v96 offset0:200 offset1:204
	ds_read2_b64 v[212:215], v97 offset0:232 offset1:236
	ds_read2_b64 v[216:219], v98 offset0:8 offset1:12
	ds_read2_b64 v[220:223], v99 offset0:40 offset1:44
	ds_read2_b64 v[224:227], v100 offset0:72 offset1:76
	ds_read2_b64 v[228:231], v101 offset0:104 offset1:108
	s_waitcnt lgkmcnt(5)
	v_mfma_f32_16x16x32_bf16 v[34:37], v[208:211], v[82:85], v[34:37]
	s_waitcnt lgkmcnt(4)
	v_mfma_f32_16x16x32_bf16 v[26:29], v[212:215], v[82:85], v[26:29]
	s_waitcnt lgkmcnt(3)
	v_mfma_f32_16x16x32_bf16 v[22:25], v[216:219], v[82:85], v[22:25]
	s_waitcnt lgkmcnt(2)
	v_mfma_f32_16x16x32_bf16 v[46:49], v[220:223], v[82:85], v[46:49]
	s_waitcnt lgkmcnt(1)
	v_mfma_f32_16x16x32_bf16 v[42:45], v[224:227], v[82:85], v[42:45]
	s_waitcnt lgkmcnt(0)
	v_mfma_f32_16x16x32_bf16 v[0:3], v[228:231], v[82:85], v[0:3]
	s_cbranch_scc1 .LBB0_1553

.LBB0_1481:
	ds_read_b128 v[82:85], v202
	ds_read_b128 v[86:89], v202 offset:64
	s_mov_b64 s[0:1], -1
	s_cmp_ge_u32 s12, s7
	s_waitcnt lgkmcnt(1)
	v_mfma_f32_16x16x32_bf16 v[82:85], v[82:85], v[38:41], 0
	ds_read_b128 v[90:93], v202 offset:4416
	ds_read_b128 v[94:97], v202 offset:8768
	ds_read_b128 v[98:101], v202 offset:13120
	s_waitcnt lgkmcnt(3)
	v_mfma_f32_16x16x32_bf16 v[82:85], v[86:89], v[30:33], v[82:85]
	ds_read_b128 v[208:211], v202 offset:128
	ds_read_b128 v[212:215], v202 offset:192
	ds_read_b128 v[216:219], v202 offset:4352
	s_waitcnt lgkmcnt(2)
	v_mfma_f32_16x16x32_bf16 v[82:85], v[208:211], v[18:21], v[82:85]
	s_waitcnt lgkmcnt(1)
	v_mfma_f32_16x16x32_bf16 v[82:85], v[212:215], v[14:17], v[82:85]
	s_waitcnt lgkmcnt(0)
	v_mfma_f32_16x16x32_bf16 v[86:89], v[216:219], v[38:41], 0
	v_mfma_f32_16x16x32_bf16 v[86:89], v[90:93], v[30:33], v[86:89]
	ds_read_b128 v[208:211], v202 offset:4480
	ds_read_b128 v[212:215], v202 offset:4544
	ds_read_b128 v[216:219], v202 offset:8704
	s_waitcnt lgkmcnt(2)
	v_mfma_f32_16x16x32_bf16 v[86:89], v[208:211], v[18:21], v[86:89]
	s_waitcnt lgkmcnt(1)
	v_mfma_f32_16x16x32_bf16 v[86:89], v[212:215], v[14:17], v[86:89]
	s_waitcnt lgkmcnt(0)
	v_mfma_f32_16x16x32_bf16 v[90:93], v[216:219], v[38:41], 0
	v_mfma_f32_16x16x32_bf16 v[90:93], v[94:97], v[30:33], v[90:93]
	ds_read_b128 v[208:211], v202 offset:8832
	ds_read_b128 v[212:215], v202 offset:8896
	ds_read_b128 v[216:219], v202 offset:13056
	s_waitcnt lgkmcnt(2)
	v_mfma_f32_16x16x32_bf16 v[90:93], v[208:211], v[18:21], v[90:93]
	s_waitcnt lgkmcnt(1)
	v_mfma_f32_16x16x32_bf16 v[90:93], v[212:215], v[14:17], v[90:93]
	s_waitcnt lgkmcnt(0)
	v_mfma_f32_16x16x32_bf16 v[94:97], v[216:219], v[38:41], 0
	v_mfma_f32_16x16x32_bf16 v[94:97], v[98:101], v[30:33], v[94:97]
	ds_read_b128 v[208:211], v202 offset:13184
	ds_read_b128 v[212:215], v202 offset:13248
	s_waitcnt lgkmcnt(1)
	v_mfma_f32_16x16x32_bf16 v[94:97], v[208:211], v[18:21], v[94:97]
	s_waitcnt lgkmcnt(0)
	v_mfma_f32_16x16x32_bf16 v[94:97], v[212:215], v[14:17], v[94:97]
	s_cbranch_scc0 .LBB0_1551
	s_cmp_gt_u32 s12, s7
	s_cbranch_scc1 .LBB0_1548
	v_add_u32_e32 v100, s9, v177
	v_cmp_gt_i32_e32 vcc, 1, v100
	s_and_saveexec_b64 s[0:1], vcc
	s_xor_b64 s[0:1], exec, s[0:1]
	s_cbranch_execz .LBB0_1485
	v_add_u32_e32 v98, s11, v179
	v_cvt_f32_u32_e32 v98, v98
	v_cmp_ne_u32_e32 vcc, s11, v177
	v_mul_f32_e32 v98, v171, v98
	v_exp_f32_e32 v98, v98
	s_nop 0
	v_cndmask_b32_e32 v98, 2.0, v98, vcc

.LBB0_3182:
	s_nop 4
	v_add_u32_e32 v94, 0x4000, v201
	ds_read2_b64 v[90:93], v94 offset0:128 offset1:132
	v_cvt_pk_bf16_f32 v86, v98, v99
	v_cvt_pk_bf16_f32 v87, v100, v101
	v_cvt_pk_bf16_f32 v88, v102, v103
	v_cvt_pk_bf16_f32 v89, v104, v105
	v_add_u32_e32 v95, 0x4800, v201
	v_add_u32_e32 v96, 0x5000, v201
	v_mul_f32_e32 v85, v97, v203
	v_add_u32_e32 v97, 0x5800, v201
	s_waitcnt lgkmcnt(0)
	v_mfma_f32_16x16x32_bf16 v[74:77], v[90:93], v[86:89], v[74:77]
	ds_read2_b64 v[90:93], v95 offset0:160 offset1:164
	v_add_u32_e32 v98, 0x6800, v201
	v_add_u32_e32 v99, 0x7000, v201
	v_add_u32_e32 v100, 0x7800, v201
	v_add_u32_e32 v101, 0x8000, v201
	v_cvt_pk_bf16_f32 v82, v106, v107
	v_cvt_pk_bf16_f32 v83, v108, v109
	v_cvt_pk_bf16_f32 v84, v164, v165
	s_waitcnt lgkmcnt(0)
	v_mfma_f32_16x16x32_bf16 v[78:81], v[90:93], v[86:89], v[78:81]
	ds_read2_b64 v[90:93], v96 offset0:192 offset1:196
	v_cvt_pk_bf16_f32 v85, v202, v85
	s_add_i32 s5, s5, 64
	s_sub_i32 s8, s8, 64
	s_add_i32 s10, s10, 1
	v_lshl_add_u64 v[156:157], v[156:157], 0, s[38:39]
	v_lshl_add_u64 v[158:159], v[158:159], 0, s[38:39]
	s_waitcnt lgkmcnt(0)
	v_mfma_f32_16x16x32_bf16 v[70:73], v[90:93], v[86:89], v[70:73]
	ds_read2_b64 v[90:93], v97 offset0:224 offset1:228
	v_lshl_add_u64 v[160:161], v[160:161], 0, s[38:39]
	v_lshl_add_u64 v[162:163], v[162:163], 0, s[38:39]
	s_cmpk_lg_i32 s5, 0x100
	s_waitcnt lgkmcnt(0)
	v_mfma_f32_16x16x32_bf16 v[66:69], v[90:93], v[86:89], v[66:69]
	ds_read2_b64 v[208:211], v98 offset1:4
	ds_read2_b64 v[212:215], v99 offset0:32 offset1:36
	ds_read2_b64 v[216:219], v100 offset0:64 offset1:68
	ds_read2_b64 v[220:223], v101 offset0:96 offset1:100
	ds_read2_b64 v[224:227], v94 offset0:136 offset1:140
	ds_read2_b64 v[228:231], v95 offset0:168 offset1:172
	s_waitcnt lgkmcnt(5)
	v_mfma_f32_16x16x32_bf16 v[62:65], v[208:211], v[86:89], v[62:65]
	s_waitcnt lgkmcnt(4)
	v_mfma_f32_16x16x32_bf16 v[58:61], v[212:215], v[86:89], v[58:61]
	s_waitcnt lgkmcnt(3)
	v_mfma_f32_16x16x32_bf16 v[54:57], v[216:219], v[86:89], v[54:57]
	s_waitcnt lgkmcnt(2)
	v_mfma_f32_16x16x32_bf16 v[0:3], v[220:223], v[86:89], v[0:3]
	s_waitcnt lgkmcnt(1)
	v_mfma_f32_16x16x32_bf16 v[74:77], v[224:227], v[82:85], v[74:77]
	s_waitcnt lgkmcnt(0)
	v_mfma_f32_16x16x32_bf16 v[78:81], v[228:231], v[82:85], v[78:81]
	ds_read2_b64 v[208:211], v96 offset0:200 offset1:204
	ds_read2_b64 v[212:215], v97 offset0:232 offset1:236
	ds_read2_b64 v[216:219], v98 offset0:8 offset1:12
	ds_read2_b64 v[220:223], v99 offset0:40 offset1:44
	ds_read2_b64 v[224:227], v100 offset0:72 offset1:76
	ds_read2_b64 v[228:231], v101 offset0:104 offset1:108
	s_waitcnt lgkmcnt(5)
	v_mfma_f32_16x16x32_bf16 v[70:73], v[208:211], v[82:85], v[70:73]
	s_waitcnt lgkmcnt(4)
	v_mfma_f32_16x16x32_bf16 v[66:69], v[212:215], v[82:85], v[66:69]
	s_waitcnt lgkmcnt(3)
	v_mfma_f32_16x16x32_bf16 v[62:65], v[216:219], v[82:85], v[62:65]
	s_waitcnt lgkmcnt(2)
	v_mfma_f32_16x16x32_bf16 v[58:61], v[220:223], v[82:85], v[58:61]
	s_waitcnt lgkmcnt(1)
	v_mfma_f32_16x16x32_bf16 v[54:57], v[224:227], v[82:85], v[54:57]
	s_waitcnt lgkmcnt(0)
	v_mfma_f32_16x16x32_bf16 v[0:3], v[228:231], v[82:85], v[0:3]
	s_cbranch_scc0 .LBB0_3257

.LBB0_3456:
	v_sub_f32_e32 v6, v6, v121
	v_mul_f32_e32 v6, 0x3fb8aa3b, v6
	v_exp_f32_e32 v6, v6
	s_andn2_b64 vcc, exec, s[58:59]
	v_add_u32_e32 v122, 0x6800, v119
	v_add_u32_e32 v78, 0x7000, v119
	v_pk_mul_f32 v[58:59], v[58:59], v[6:7] op_sel_hi:[1,0]
	v_pk_mul_f32 v[56:57], v[56:57], v[6:7] op_sel_hi:[1,0]
	v_pk_mul_f32 v[54:55], v[54:55], v[6:7] op_sel_hi:[1,0]
	v_pk_mul_f32 v[52:53], v[52:53], v[6:7] op_sel_hi:[1,0]
	v_pk_mul_f32 v[50:51], v[50:51], v[6:7] op_sel_hi:[1,0]
	v_pk_mul_f32 v[48:49], v[48:49], v[6:7] op_sel_hi:[1,0]
	v_pk_mul_f32 v[46:47], v[46:47], v[6:7] op_sel_hi:[1,0]
	v_pk_mul_f32 v[44:45], v[44:45], v[6:7] op_sel_hi:[1,0]
	v_add_u32_e32 v74, 0x7800, v119
	v_add_u32_e32 v62, 0x8000, v119
	s_cbranch_vccnz .LBB0_3458
	ds_read2_b64 v[128:131], v122 offset0:128 offset1:132
	v_cvt_pk_bf16_f32 v124, v69, v71
	v_cvt_pk_bf16_f32 v125, v76, v77
	v_cvt_pk_bf16_f32 v126, v65, v73
	v_cvt_pk_bf16_f32 v127, v75, v79
	s_waitcnt lgkmcnt(0)
	s_nop 0
	v_mfma_f32_16x16x32_bf16 v[56:59], v[128:131], v[124:127], v[56:59]
	ds_read2_b64 v[132:135], v78 offset0:160 offset1:164
	ds_read2_b64 v[136:139], v74 offset0:192 offset1:196
	ds_read2_b64 v[140:143], v62 offset0:224 offset1:228
	s_waitcnt lgkmcnt(2)
	v_mfma_f32_16x16x32_bf16 v[52:55], v[132:135], v[124:127], v[52:55]
	s_waitcnt lgkmcnt(1)
	v_mfma_f32_16x16x32_bf16 v[48:51], v[136:139], v[124:127], v[48:51]
	s_waitcnt lgkmcnt(0)
	v_mfma_f32_16x16x32_bf16 v[44:47], v[140:143], v[124:127], v[44:47]

.LBB0_3466:
	s_nop 4
	v_add_u32_e32 v94, 0x4000, v203
	ds_read2_b64 v[90:93], v94 offset0:128 offset1:132
	v_cvt_pk_bf16_f32 v86, v98, v99
	v_cvt_pk_bf16_f32 v87, v100, v101
	v_cvt_pk_bf16_f32 v88, v102, v103
	v_cvt_pk_bf16_f32 v89, v104, v105
	v_add_u32_e32 v95, 0x4800, v203
	v_add_u32_e32 v96, 0x5000, v203
	v_mul_f32_e32 v85, v97, v205
	v_add_u32_e32 v97, 0x5800, v203
	s_waitcnt lgkmcnt(0)
	v_mfma_f32_16x16x32_bf16 v[6:9], v[90:93], v[86:89], v[6:9]
	ds_read2_b64 v[90:93], v95 offset0:160 offset1:164
	v_add_u32_e32 v98, 0x6800, v203
	v_add_u32_e32 v99, 0x7000, v203
	v_add_u32_e32 v100, 0x7800, v203
	v_add_u32_e32 v101, 0x8000, v203
	v_cvt_pk_bf16_f32 v82, v106, v107
	v_cvt_pk_bf16_f32 v83, v108, v109
	v_cvt_pk_bf16_f32 v84, v166, v167
	s_waitcnt lgkmcnt(0)
	v_mfma_f32_16x16x32_bf16 v[10:13], v[90:93], v[86:89], v[10:13]
	ds_read2_b64 v[90:93], v96 offset0:192 offset1:196
	v_cvt_pk_bf16_f32 v85, v204, v85
	s_add_i32 s11, s11, 64
	s_sub_i32 s9, s9, 64
	s_add_i32 s12, s12, 1
	v_lshl_add_u64 v[158:159], v[158:159], 0, s[38:39]
	v_lshl_add_u64 v[160:161], v[160:161], 0, s[38:39]
	s_waitcnt lgkmcnt(0)
	v_mfma_f32_16x16x32_bf16 v[30:33], v[90:93], v[86:89], v[30:33]
	ds_read2_b64 v[90:93], v97 offset0:224 offset1:228
	v_lshl_add_u64 v[162:163], v[162:163], 0, s[38:39]
	v_lshl_add_u64 v[164:165], v[164:165], 0, s[38:39]
	s_cmpk_eq_i32 s11, 0x400
	s_waitcnt lgkmcnt(0)
	v_mfma_f32_16x16x32_bf16 v[26:29], v[90:93], v[86:89], v[26:29]
	ds_read2_b64 v[208:211], v98 offset1:4
	ds_read2_b64 v[212:215], v99 offset0:32 offset1:36
	ds_read2_b64 v[216:219], v100 offset0:64 offset1:68
	ds_read2_b64 v[220:223], v101 offset0:96 offset1:100
	ds_read2_b64 v[224:227], v94 offset0:136 offset1:140
	ds_read2_b64 v[228:231], v95 offset0:168 offset1:172
	s_waitcnt lgkmcnt(5)
	v_mfma_f32_16x16x32_bf16 v[22:25], v[208:211], v[86:89], v[22:25]
	s_waitcnt lgkmcnt(4)
	v_mfma_f32_16x16x32_bf16 v[46:49], v[212:215], v[86:89], v[46:49]
	s_waitcnt lgkmcnt(3)
	v_mfma_f32_16x16x32_bf16 v[42:45], v[216:219], v[86:89], v[42:45]
	s_waitcnt lgkmcnt(2)
	v_mfma_f32_16x16x32_bf16 v[0:3], v[220:223], v[86:89], v[0:3]
	s_waitcnt lgkmcnt(1)
	v_mfma_f32_16x16x32_bf16 v[6:9], v[224:227], v[82:85], v[6:9]
	s_waitcnt lgkmcnt(0)
	v_mfma_f32_16x16x32_bf16 v[10:13], v[228:231], v[82:85], v[10:13]
	ds_read2_b64 v[208:211], v96 offset0:200 offset1:204
	ds_read2_b64 v[212:215], v97 offset0:232 offset1:236
	ds_read2_b64 v[216:219], v98 offset0:8 offset1:12
	ds_read2_b64 v[220:223], v99 offset0:40 offset1:44
	ds_read2_b64 v[224:227], v100 offset0:72 offset1:76
	ds_read2_b64 v[228:231], v101 offset0:104 offset1:108
	s_waitcnt lgkmcnt(5)
	v_mfma_f32_16x16x32_bf16 v[30:33], v[208:211], v[82:85], v[30:33]
	s_waitcnt lgkmcnt(4)
	v_mfma_f32_16x16x32_bf16 v[26:29], v[212:215], v[82:85], v[26:29]
	s_waitcnt lgkmcnt(3)
	v_mfma_f32_16x16x32_bf16 v[22:25], v[216:219], v[82:85], v[22:25]
	s_waitcnt lgkmcnt(2)
	v_mfma_f32_16x16x32_bf16 v[46:49], v[220:223], v[82:85], v[46:49]
	s_waitcnt lgkmcnt(1)
	v_mfma_f32_16x16x32_bf16 v[42:45], v[224:227], v[82:85], v[42:45]
	s_waitcnt lgkmcnt(0)
	v_mfma_f32_16x16x32_bf16 v[0:3], v[228:231], v[82:85], v[0:3]
	s_cbranch_scc1 .LBB0_3541

.LBB0_3469:
	ds_read_b128 v[82:85], v202
	ds_read_b128 v[86:89], v202 offset:64
	s_mov_b64 s[0:1], -1
	s_cmp_ge_u32 s12, s7
	s_waitcnt lgkmcnt(1)
	v_mfma_f32_16x16x32_bf16 v[82:85], v[82:85], v[38:41], 0
	ds_read_b128 v[90:93], v202 offset:4416
	ds_read_b128 v[94:97], v202 offset:8768
	ds_read_b128 v[98:101], v202 offset:13120
	s_waitcnt lgkmcnt(3)
	v_mfma_f32_16x16x32_bf16 v[82:85], v[86:89], v[34:37], v[82:85]
	ds_read_b128 v[208:211], v202 offset:128
	ds_read_b128 v[212:215], v202 offset:192
	ds_read_b128 v[216:219], v202 offset:4352
	s_waitcnt lgkmcnt(2)
	v_mfma_f32_16x16x32_bf16 v[82:85], v[208:211], v[18:21], v[82:85]
	s_waitcnt lgkmcnt(1)
	v_mfma_f32_16x16x32_bf16 v[82:85], v[212:215], v[14:17], v[82:85]
	s_waitcnt lgkmcnt(0)
	v_mfma_f32_16x16x32_bf16 v[86:89], v[216:219], v[38:41], 0
	v_mfma_f32_16x16x32_bf16 v[86:89], v[90:93], v[34:37], v[86:89]
	ds_read_b128 v[208:211], v202 offset:4480
	ds_read_b128 v[212:215], v202 offset:4544
	ds_read_b128 v[216:219], v202 offset:8704
	s_waitcnt lgkmcnt(2)
	v_mfma_f32_16x16x32_bf16 v[86:89], v[208:211], v[18:21], v[86:89]
	s_waitcnt lgkmcnt(1)
	v_mfma_f32_16x16x32_bf16 v[86:89], v[212:215], v[14:17], v[86:89]
	s_waitcnt lgkmcnt(0)
	v_mfma_f32_16x16x32_bf16 v[90:93], v[216:219], v[38:41], 0
	v_mfma_f32_16x16x32_bf16 v[90:93], v[94:97], v[34:37], v[90:93]
	ds_read_b128 v[208:211], v202 offset:8832
	ds_read_b128 v[212:215], v202 offset:8896
	ds_read_b128 v[216:219], v202 offset:13056
	s_waitcnt lgkmcnt(2)
	v_mfma_f32_16x16x32_bf16 v[90:93], v[208:211], v[18:21], v[90:93]
	s_waitcnt lgkmcnt(1)
	v_mfma_f32_16x16x32_bf16 v[90:93], v[212:215], v[14:17], v[90:93]
	s_waitcnt lgkmcnt(0)
	v_mfma_f32_16x16x32_bf16 v[94:97], v[216:219], v[38:41], 0
	v_mfma_f32_16x16x32_bf16 v[94:97], v[98:101], v[34:37], v[94:97]
	ds_read_b128 v[208:211], v202 offset:13184
	ds_read_b128 v[212:215], v202 offset:13248
	s_waitcnt lgkmcnt(1)
	v_mfma_f32_16x16x32_bf16 v[94:97], v[208:211], v[18:21], v[94:97]
	s_waitcnt lgkmcnt(0)
	v_mfma_f32_16x16x32_bf16 v[94:97], v[212:215], v[14:17], v[94:97]
	s_cbranch_scc0 .LBB0_3539
	s_cmp_gt_u32 s12, s7
	s_cbranch_scc1 .LBB0_3536
	v_add_u32_e32 v100, s9, v177
	v_cmp_gt_i32_e32 vcc, 1, v100
	s_and_saveexec_b64 s[0:1], vcc
	s_xor_b64 s[0:1], exec, s[0:1]
	s_cbranch_execz .LBB0_3473
	v_add_u32_e32 v98, s11, v179
	v_cvt_f32_u32_e32 v98, v98
	v_cmp_ne_u32_e32 vcc, s11, v177
	v_mul_f32_e32 v98, v171, v98
	v_exp_f32_e32 v98, v98
	s_nop 0
	v_cndmask_b32_e32 v98, 2.0, v98, vcc
